# v28 + attention row sums via v_pk_add_f32 over aligned pairs (32 fewer VALU per sub-tile)
# baseline (speedup 1.0000x reference)
; #define LAS __attribute__((address_space(3)))
; __device__ __forceinline__ unsigned pk2(float lo, float hi) { f32x2 v = {lo, hi}; nbf2 r = __builtin_convertvector(v, nbf2); return __builtin_bit_cast(unsigned, r); }
; __device__ __forceinline__ float fast_exp2(float x) { return __builtin_amdgcn_exp2f(x); }
; #define MFMA32(a, b, c) __builtin_amdgcn_mfma_f32_32x32x16_bf16((a), (b), (c), 0, 0, 0)
; __device__ __forceinline__ void attn_phase(LAS unsigned char* lds, const bf16_t* QKVZ, bf16_t* AO, const float* sink) {
;     ...
;                     float rs = 0.f;
; #pragma unroll
;                     for (int kt = 0; kt < 2; ++kt)
; #pragma unroll
;                         for (int i = 0; i < 16; ++i) { const float p = fast_exp2(S[kt][qt][i]); S[kt][qt][i] = p; rs += p; }
;                     l_[qt] = l_[qt] * alpha + rs;
;                 }
; #pragma unroll
;                 for (int kt = 0; kt < 2; ++kt)
; #pragma unroll
;                     for (int s2 = 0; s2 < 2; ++s2) {
;                         bf16x8 Pf[2];
; #pragma unroll
;                         for (int qt = 0; qt < 2; ++qt) {
;                             u32x4 w; w.x = pk2(S[kt][qt][8 * s2 + 0], S[kt][qt][8 * s2 + 1]); w.y = pk2(S[kt][qt][8 * s2 + 2], S[kt][qt][8 * s2 + 3]);
;                             w.z = pk2(S[kt][qt][8 * s2 + 4], S[kt][qt][8 * s2 + 5]); w.w = pk2(S[kt][qt][8 * s2 + 6], S[kt][qt][8 * s2 + 7]);
;                             Pf[qt] = __builtin_bit_cast(bf16x8, w);
;                         }
; #pragma unroll
;                         for (int dt = 0; dt < 2; ++dt) {
;                             const LAS unsigned char* ap = Vt + (32 * dt + ql) * VT_PITCH + (64 * sub + 32 * kt + 16 * s2 + 4 * hh) * 2;
;                             const u32x2 lo = *(const LAS u32x2*)ap, hi = *(const LAS u32x2*)(ap + 16);
;                             u32x4 w; w.x = lo.x; w.y = lo.y; w.z = hi.x; w.w = hi.y;
;                             const bf16x8 Vf = __builtin_bit_cast(bf16x8, w);
;                             O[dt][0] = MFMA32(Vf, Pf[0], O[dt][0]);
;                             O[dt][1] = MFMA32(Vf, Pf[1], O[dt][1]);
;                         }
.LBB0_309:
	v_exp_f32_e32 v128, v128
	v_exp_f32_e32 v129, v129
	v_exp_f32_e32 v130, v130
	v_exp_f32_e32 v131, v131
	v_exp_f32_e32 v132, v132
	v_exp_f32_e32 v133, v133
	v_exp_f32_e32 v134, v134
	v_pk_add_f32 v[246:247], v[128:129], v[130:131]
	v_exp_f32_e32 v135, v135
	v_exp_f32_e32 v136, v136
	v_pk_add_f32 v[246:247], v[246:247], v[132:133]
	v_exp_f32_e32 v137, v137
	v_exp_f32_e32 v138, v138
	v_pk_add_f32 v[246:247], v[246:247], v[134:135]
	v_exp_f32_e32 v139, v139
	v_exp_f32_e32 v140, v140
	v_pk_add_f32 v[246:247], v[246:247], v[136:137]
	v_exp_f32_e32 v141, v141
	v_exp_f32_e32 v142, v142
	v_pk_add_f32 v[246:247], v[246:247], v[138:139]
	v_exp_f32_e32 v143, v143
	v_exp_f32_e32 v240, v96
	v_pk_add_f32 v[246:247], v[246:247], v[140:141]
	v_exp_f32_e32 v241, v97
	v_exp_f32_e32 v228, v98
	v_pk_add_f32 v[246:247], v[246:247], v[142:143]
	v_exp_f32_e32 v229, v99
	v_exp_f32_e32 v230, v100
	v_pk_add_f32 v[246:247], v[246:247], v[240:241]
	v_exp_f32_e32 v231, v101
	v_exp_f32_e32 v232, v102
	v_pk_add_f32 v[246:247], v[246:247], v[228:229]
	v_exp_f32_e32 v233, v103
	v_exp_f32_e32 v242, v104
	v_pk_add_f32 v[246:247], v[246:247], v[230:231]
	v_lshl_add_u32 v104, s75, 7, v11
	v_pk_add_f32 v[246:247], v[246:247], v[232:233]
	v_add_u32_e32 v239, 0x4800, v104
	ds_read2_b64 v[12:15], v239 offset1:2
	v_exp_f32_e32 v112, v112
	v_exp_f32_e32 v113, v113
	v_exp_f32_e32 v114, v114
	v_exp_f32_e32 v115, v115
	v_exp_f32_e32 v116, v116
	v_exp_f32_e32 v117, v117
	v_exp_f32_e32 v118, v118
	v_exp_f32_e32 v119, v119
	v_exp_f32_e32 v243, v105
	v_cvt_pk_bf16_f32 v96, v128, v129
	v_add_u32_e32 v128, 0x6800, v104
	v_exp_f32_e32 v244, v106
	v_exp_f32_e32 v245, v107
	ds_read2_b64 v[104:107], v128 offset0:32 offset1:34
	v_exp_f32_e32 v108, v108
	v_cvt_pk_bf16_f32 v97, v130, v131
	v_cvt_pk_bf16_f32 v98, v132, v133
	v_cvt_pk_bf16_f32 v99, v134, v135
	v_cvt_pk_bf16_f32 v100, v112, v113
	v_cvt_pk_bf16_f32 v101, v114, v115
	v_cvt_pk_bf16_f32 v102, v116, v117
	v_cvt_pk_bf16_f32 v103, v118, v119
	s_waitcnt lgkmcnt(1)
	v_mfma_f32_32x32x16_bf16 v[64:79], v[12:15], v[96:99], v[64:79]
	v_exp_f32_e32 v109, v109
	v_exp_f32_e32 v110, v110
	v_exp_f32_e32 v111, v111
	v_exp_f32_e32 v120, v120
	v_exp_f32_e32 v121, v121
	v_exp_f32_e32 v122, v122
	v_exp_f32_e32 v123, v123
	v_mfma_f32_32x32x16_bf16 v[32:47], v[12:15], v[100:103], v[32:47]
	v_pk_add_f32 v[246:247], v[246:247], v[242:243]
	v_pk_add_f32 v[246:247], v[246:247], v[244:245]
	v_pk_add_f32 v[246:247], v[246:247], v[108:109]
	v_pk_add_f32 v[246:247], v[246:247], v[110:111]
	v_add_f32_e32 v129, v246, v247
	s_waitcnt lgkmcnt(0)
	v_mfma_f32_32x32x16_bf16 v[48:63], v[104:107], v[96:99], v[48:63]
	ds_read2_b64 v[12:15], v239 offset0:4 offset1:6
	v_fmac_f32_e32 v129, v1, v8
	v_exp_f32_e32 v124, v124
	v_exp_f32_e32 v125, v125
	v_mfma_f32_32x32x16_bf16 v[16:31], v[104:107], v[100:103], v[16:31]
	ds_read2_b64 v[104:107], v128 offset0:36 offset1:38
	v_exp_f32_e32 v126, v126
	v_exp_f32_e32 v127, v127
	v_pk_add_f32 v[246:247], v[112:113], v[114:115]
	v_pk_add_f32 v[246:247], v[246:247], v[116:117]
	v_cvt_pk_bf16_f32 v96, v136, v137
	v_cvt_pk_bf16_f32 v97, v138, v139
	v_cvt_pk_bf16_f32 v98, v140, v141
	v_cvt_pk_bf16_f32 v99, v142, v143
	v_cvt_pk_bf16_f32 v100, v120, v121
	v_cvt_pk_bf16_f32 v101, v122, v123
	v_cvt_pk_bf16_f32 v102, v124, v125
	v_cvt_pk_bf16_f32 v103, v126, v127
	v_pk_add_f32 v[246:247], v[246:247], v[118:119]
	s_waitcnt lgkmcnt(1)
	v_mfma_f32_32x32x16_bf16 v[64:79], v[12:15], v[96:99], v[64:79]
	v_pk_add_f32 v[246:247], v[246:247], v[120:121]
	v_pk_add_f32 v[246:247], v[246:247], v[122:123]
	v_exp_f32_e32 v248, v80
	v_exp_f32_e32 v249, v81
	v_exp_f32_e32 v250, v82
	v_mfma_f32_32x32x16_bf16 v[32:47], v[12:15], v[100:103], v[32:47]
	ds_read2_b64 v[12:15], v239 offset0:8 offset1:10
	v_pk_add_f32 v[246:247], v[246:247], v[124:125]
	v_pk_add_f32 v[246:247], v[246:247], v[126:127]
	v_cvt_pk_bf16_f32 v80, v240, v241
	v_cvt_pk_bf16_f32 v81, v228, v229
	s_waitcnt lgkmcnt(1)
	v_mfma_f32_32x32x16_bf16 v[48:63], v[104:107], v[96:99], v[48:63]
	ds_read2_b64 v[96:99], v128 offset0:40 offset1:42
	v_cvt_pk_bf16_f32 v82, v230, v231
	v_pk_add_f32 v[246:247], v[246:247], v[248:249]
	v_exp_f32_e32 v92, v92
	v_exp_f32_e32 v93, v93
	v_mfma_f32_32x32x16_bf16 v[16:31], v[104:107], v[100:103], v[16:31]
	v_exp_f32_e32 v251, v83
	v_exp_f32_e32 v240, v84
	v_exp_f32_e32 v241, v85
	v_exp_f32_e32 v228, v86
	v_exp_f32_e32 v229, v87
	v_cvt_pk_bf16_f32 v83, v232, v233
	v_cvt_pk_bf16_f32 v84, v248, v249
	v_cvt_pk_bf16_f32 v85, v250, v251
	v_cvt_pk_bf16_f32 v86, v240, v241
	v_cvt_pk_bf16_f32 v87, v228, v229
	s_waitcnt lgkmcnt(1)
	v_mfma_f32_32x32x16_bf16 v[64:79], v[12:15], v[80:83], v[64:79]
	v_exp_f32_e32 v230, v88
	v_exp_f32_e32 v231, v89
	v_exp_f32_e32 v232, v90
	v_pk_add_f32 v[246:247], v[246:247], v[250:251]
	v_exp_f32_e32 v94, v94
	v_exp_f32_e32 v95, v95
	v_mfma_f32_32x32x16_bf16 v[32:47], v[12:15], v[84:87], v[32:47]
	ds_read2_b64 v[12:15], v239 offset0:12 offset1:14
	v_pk_add_f32 v[246:247], v[246:247], v[240:241]
	v_pk_add_f32 v[246:247], v[246:247], v[228:229]
	v_pk_add_f32 v[246:247], v[246:247], v[230:231]
	s_waitcnt lgkmcnt(1)
	v_mfma_f32_32x32x16_bf16 v[48:63], v[96:99], v[80:83], v[48:63]
	v_cvt_pk_bf16_f32 v80, v242, v243
	v_cvt_pk_bf16_f32 v81, v244, v245
	v_cvt_pk_bf16_f32 v82, v108, v109
	v_cvt_pk_bf16_f32 v83, v110, v111
	v_mfma_f32_32x32x16_bf16 v[16:31], v[96:99], v[84:87], v[16:31]
	v_exp_f32_e32 v233, v91
	ds_read2_b64 v[88:91], v128 offset0:44 offset1:46
	v_cvt_pk_bf16_f32 v84, v230, v231
	v_cvt_pk_bf16_f32 v86, v92, v93
	v_cvt_pk_bf16_f32 v85, v232, v233
	v_cvt_pk_bf16_f32 v87, v94, v95
	v_pk_add_f32 v[246:247], v[246:247], v[232:233]
	s_waitcnt lgkmcnt(1)
	v_mfma_f32_32x32x16_bf16 v[64:79], v[12:15], v[80:83], v[64:79]
	v_pk_add_f32 v[246:247], v[246:247], v[92:93]
	v_pk_add_f32 v[246:247], v[246:247], v[94:95]
	v_add_f32_e32 v8, v246, v247
	v_fmac_f32_e32 v8, v227, v6
	v_mov_b32_e32 v1, v129
	v_mov_b32_e32 v227, v8
	v_mfma_f32_32x32x16_bf16 v[32:47], v[12:15], v[84:87], v[32:47]
	s_waitcnt lgkmcnt(0)
	v_mfma_f32_32x32x16_bf16 v[48:63], v[88:91], v[80:83], v[48:63]
	v_mfma_f32_32x32x16_bf16 v[16:31], v[88:91], v[84:87], v[16:31]
